# mix-phase units no longer drain the previous unit's store acks before issuing their first loads
# speedup vs baseline: 1.0058x; 1.0058x over previous
; #define LAS __attribute__((address_space(3)))
; __device__ __forceinline__ unsigned cvt_pk_bf16(float lo, float hi) { unsigned r; asm volatile("v_cvt_pk_bf16_f32 %0, %1, %2" : "=v"(r) : "v"(lo), "v"(hi)); return r; }
; __device__ __forceinline__ void gmlp_unit(LAS unsigned char* lds, const bf16_t* __restrict__ UV, const bf16_t* __restrict__ Wsb  , const float* __restrict__ gain  ,
;                                           const float* __restrict__ bs  , int r0, int h, bf16_t* __restrict__ O, int tid) {
;     constexpr int VP = 136;
;     LAS bf16_t* vT = (LAS bf16_t*)lds;
;     const int lane = tid & 63, w = tid >> 6, fr = lane & 15, fq = lane >> 4;
;     {
;         const int q = tid >> 2, part = tid & 3;
;         const bf16_t* src = UV + (size_t)(r0 + q) * 512 + 256 + 64 * h + 16 * part;
;         const u32x4 a0 = *(const u32x4*)src, a1 = *(const u32x4*)(src + 8);
;         float v[16];
; #pragma unroll
;         for (int i = 0; i < 4; ++i) { v[2 * i] = __uint_as_float(a0[i] << 16); v[2 * i + 1] = __uint_as_float(a0[i] & 0xffff0000u); v[8 + 2 * i] = __uint_as_float(a1[i] << 16); v[8 + 2 * i + 1] = __uint_as_float(a1[i] & 0xffff0000u); }
;         float ss = 0.f;
; #pragma unroll
;         for (int i = 0; i < 16; ++i) ss += v[i] * v[i];
;         ss += __shfl_xor(ss, 1); ss += __shfl_xor(ss, 2);
;         const float rstd = rsqrtf(ss * (1.0f / 64.0f) + EPSV);
; #pragma unroll
;         for (int i = 0; i < 16; ++i) { const int c = 16 * part + i; vT[c * VP + q] = (bf16_t)(cvt_pk_bf16(v[i] * rstd * gain[c], 0.f) & 0xffffu); }
.LBB0_106:
	v_mov_b32_e32 v176, v158
	s_mov_b64 s[0:1], -1
	v_ashrrev_i32_e32 v174, 2, v176
	v_bfe_u32 v177, v176, 4, 2
	s_cmp_ge_i32 s22, s18
	v_and_b32_e32 v173, 15, v176
	v_bfi_b32 v160, -16, v174, v176
	v_lshlrev_b32_e32 v162, 4, v177
	s_cbranch_scc0 .LBB0_108
	s_and_b32 s14, s22, 3
	s_or_b32 s0, s14, s19
	s_ashr_i32 s1, s0, 31
	s_sub_i32 s3, s22, s18
	s_lshl_b64 s[8:9], s[0:1], 15
	v_readlane_b32 s10, v252, 16
	v_readlane_b32 s11, v252, 17
	s_add_u32 s8, s10, s8
	s_addc_u32 s9, s11, s9
	s_lshl_b32 s10, s0, 6
	s_ashr_i32 s11, s10, 31
	v_readlane_b32 s40, v254, 11
	s_lshl_b64 s[10:11], s[10:11], 2
	v_readlane_b32 s50, v254, 21
	v_readlane_b32 s51, v254, 22
	s_add_u32 s10, s50, s10
	s_addc_u32 s11, s51, s11
	s_lshl_b32 s0, s0, 7
	s_ashr_i32 s1, s0, 31
	v_readlane_b32 s54, v254, 25
	s_lshl_b64 s[0:1], s[0:1], 2
	v_readlane_b32 s55, v254, 26
	s_add_u32 s0, s54, s0
	s_addc_u32 s1, s55, s1
	s_lshl_b32 s3, s3, 5
	s_and_b32 s3, s3, 0x7fffff80
	s_waitcnt lgkmcnt(0)
	v_add_u32_e32 v2, s3, v174
	v_ashrrev_i32_e32 v3, 31, v2
	v_readlane_b32 s20, v252, 41
	v_lshlrev_b64 v[2:3], 10, v[2:3]
	v_readlane_b32 s21, v252, 42
	v_lshlrev_b32_e32 v0, 4, v176
	s_lshl_b32 s16, s14, 7
	v_lshl_add_u64 v[2:3], s[20:21], 0, v[2:3]
	s_nop 0
	v_and_b32_e32 v17, 48, v0
	v_lshl_add_u64 v[2:3], v[2:3], 0, s[16:17]
	v_lshlrev_b32_e32 v0, 1, v17
	v_lshl_add_u64 v[2:3], v[2:3], 0, v[0:1]
	global_load_dwordx4 v[20:23], v[2:3], off offset:528
	s_nop 0
	global_load_dwordx4 v[2:5], v[2:3], off offset:512
	v_xor_b32_e32 v19, 1, v191
	v_ashrrev_i32_e32 v161, 31, v160
	v_mov_b32_e32 v163, v1
	v_readlane_b32 s41, v254, 12
	v_readlane_b32 s42, v254, 13
	v_readlane_b32 s43, v254, 14
	v_readlane_b32 s44, v254, 15
	v_readlane_b32 s45, v254, 16
	v_readlane_b32 s46, v254, 17
	v_readlane_b32 s47, v254, 18
	v_readlane_b32 s48, v254, 19
	v_readlane_b32 s49, v254, 20
	v_readlane_b32 s52, v254, 23
	v_readlane_b32 s53, v254, 24
	s_waitcnt vmcnt(1)
	v_and_b32_e32 v8, 0xffff0000, v20
	s_waitcnt vmcnt(0)
	v_and_b32_e32 v18, 0xffff0000, v2
	v_lshlrev_b32_e32 v16, 16, v2
	v_mul_f32_e32 v0, v18, v18
	v_lshlrev_b32_e32 v15, 16, v3
	v_fmac_f32_e32 v0, v16, v16
	v_and_b32_e32 v14, 0xffff0000, v3
	v_fmac_f32_e32 v0, v15, v15
	v_lshlrev_b32_e32 v13, 16, v4
	v_fmac_f32_e32 v0, v14, v14
	v_and_b32_e32 v12, 0xffff0000, v4
	v_fmac_f32_e32 v0, v13, v13
	v_lshlrev_b32_e32 v11, 16, v5
	v_fmac_f32_e32 v0, v12, v12
	v_and_b32_e32 v10, 0xffff0000, v5
	v_fmac_f32_e32 v0, v11, v11
	v_lshlrev_b32_e32 v9, 16, v20
	v_fmac_f32_e32 v0, v10, v10
	v_pk_mul_f32 v[2:3], v[8:9], v[8:9]
	v_and_b32_e32 v6, 0xffff0000, v21
	v_add_f32_e32 v0, v3, v0
	v_lshlrev_b32_e32 v7, 16, v21
	v_add_f32_e32 v0, v2, v0
	v_pk_mul_f32 v[2:3], v[6:7], v[6:7]
	v_and_b32_e32 v4, 0xffff0000, v22
	v_add_f32_e32 v0, v3, v0
	v_lshlrev_b32_e32 v5, 16, v22
	v_add_f32_e32 v0, v2, v0
	v_pk_mul_f32 v[2:3], v[4:5], v[4:5]
	s_nop 0
	v_add_f32_e32 v0, v3, v0
	v_add_f32_e32 v0, v2, v0
	v_and_b32_e32 v2, 0xffff0000, v23
	v_lshlrev_b32_e32 v3, 16, v23
	v_pk_mul_f32 v[20:21], v[2:3], v[2:3]
	s_nop 0
	v_add_f32_e32 v0, v21, v0
	v_add_f32_e32 v0, v20, v0
	v_and_b32_e32 v20, 64, v191
	v_add_u32_e32 v20, 64, v20
	v_cmp_lt_i32_e32 vcc, v19, v20
	s_nop 1
	v_cndmask_b32_e32 v19, v191, v19, vcc
	v_lshlrev_b32_e32 v19, 2, v19
	ds_bpermute_b32 v19, v19, v0
	s_waitcnt lgkmcnt(0)
	v_add_f32_e32 v0, v0, v19
	v_xor_b32_e32 v19, 2, v191
	v_cmp_lt_i32_e32 vcc, v19, v20
	s_nop 1
	v_cndmask_b32_e32 v19, v191, v19, vcc
	v_lshlrev_b32_e32 v19, 2, v19
	ds_bpermute_b32 v19, v19, v0
	s_waitcnt lgkmcnt(0)
	v_add_f32_e32 v0, v0, v19
	v_fmamk_f32 v0, v0, 0x3c800000, v185
	v_cmp_gt_f32_e32 vcc, s33, v0
	v_mul_f32_e32 v19, 0x4b800000, v0
	s_nop 0
	v_cndmask_b32_e32 v0, v0, v19, vcc
	v_rsq_f32_e32 v0, v0
	s_nop 0
	v_mul_f32_e32 v19, 0x45800000, v0
	v_cndmask_b32_e32 v0, v0, v19, vcc
	v_mul_f32_e32 v20, v0, v16
	v_lshlrev_b32_e32 v16, 2, v17
	global_load_dword v21, v16, s[10:11]
	v_lshlrev_b32_e32 v19, 1, v174
	v_mul_u32_u24_e32 v17, 0x110, v17
	v_add3_u32 v17, 0, v19, v17
	v_mul_f32_e32 v18, v0, v18
	v_mul_f32_e32 v15, v0, v15
	v_mul_f32_e32 v14, v0, v14
	v_mul_f32_e32 v13, v0, v13
	v_mul_f32_e32 v12, v0, v12
	v_mul_f32_e32 v11, v0, v11
	v_mul_f32_e32 v10, v0, v10
	v_mul_f32_e32 v9, v0, v9
	v_mul_f32_e32 v8, v0, v8
	v_mul_f32_e32 v7, v0, v7
	v_mul_f32_e32 v6, v0, v6
	v_mul_f32_e32 v5, v0, v5
	v_mul_f32_e32 v4, v0, v4
	v_mul_f32_e32 v3, v0, v3
	v_mul_f32_e32 v0, v0, v2
	s_waitcnt vmcnt(0)
	v_mul_f32_e32 v20, v21, v20
	v_cvt_pk_bf16_f32 v20, v20, v1
	global_load_dword v19, v16, s[10:11] offset:4
	ds_write_b16 v17, v20
	s_waitcnt vmcnt(0)
	v_mul_f32_e32 v18, v19, v18
	v_cvt_pk_bf16_f32 v18, v18, v1
	ds_write_b16 v17, v18 offset:272
	global_load_dword v18, v16, s[10:11] offset:8
	s_waitcnt vmcnt(0)
	v_mul_f32_e32 v15, v18, v15
	v_cvt_pk_bf16_f32 v15, v15, v1
	ds_write_b16 v17, v15 offset:544
	global_load_dword v15, v16, s[10:11] offset:12
	s_waitcnt vmcnt(0)
	v_mul_f32_e32 v14, v15, v14
	v_cvt_pk_bf16_f32 v14, v14, v1
	ds_write_b16 v17, v14 offset:816
	global_load_dword v14, v16, s[10:11] offset:16
	s_waitcnt vmcnt(0)
	v_mul_f32_e32 v13, v14, v13
	v_cvt_pk_bf16_f32 v13, v13, v1
	ds_write_b16 v17, v13 offset:1088
	global_load_dword v13, v16, s[10:11] offset:20
	s_waitcnt vmcnt(0)
	v_mul_f32_e32 v12, v13, v12
	v_cvt_pk_bf16_f32 v12, v12, v1
	ds_write_b16 v17, v12 offset:1360
	global_load_dword v12, v16, s[10:11] offset:24
	s_waitcnt vmcnt(0)
	v_mul_f32_e32 v11, v12, v11
	v_cvt_pk_bf16_f32 v11, v11, v1
	ds_write_b16 v17, v11 offset:1632
	global_load_dword v11, v16, s[10:11] offset:28
	s_waitcnt vmcnt(0)
	v_mul_f32_e32 v10, v11, v10
	v_cvt_pk_bf16_f32 v10, v10, v1
	ds_write_b16 v17, v10 offset:1904
	global_load_dword v10, v16, s[10:11] offset:32
	s_waitcnt vmcnt(0)
; #define LAS __attribute__((address_space(3)))
; __device__ __forceinline__ unsigned cvt_pk_bf16(float lo, float hi) { unsigned r; asm volatile("v_cvt_pk_bf16_f32 %0, %1, %2" : "=v"(r) : "v"(lo), "v"(hi)); return r; }
; __device__ __forceinline__ void gmlp_unit(LAS unsigned char* lds, const bf16_t* __restrict__ UV, const bf16_t* __restrict__ Wsb  , const float* __restrict__ gain  ,
;                                           const float* __restrict__ bs  , int r0, int h, bf16_t* __restrict__ O, int tid) {
;     ...
;         for (int i = 0; i < 16; ++i) { const int c = 16 * part + i; vT[c * VP + q] = (bf16_t)(cvt_pk_bf16(v[i] * rstd * gain[c], 0.f) & 0xffffu); }
;     }
;     __syncthreads();
;     f32x4 acc[4];
; #pragma unroll
;     for (int nt = 0; nt < 4; ++nt) acc[nt] = (f32x4){0.f, 0.f, 0.f, 0.f};
; #pragma unroll
;     for (int ks = 0; ks < 4; ++ks) {
;         const bf16x8 wf = *(const bf16x8*)(Wsb + (size_t)(16 * w + fr) * 128 + 32 * ks + 8 * fq);
; #pragma unroll
;         for (int nt = 0; nt < 4; ++nt) { const bf16x8 vf = *(const LAS bf16x8*)(vT + (16 * nt + fr) * VP + 32 * ks + 8 * fq);
;             acc[nt] = __builtin_amdgcn_mfma_f32_16x16x32_bf16(vf, wf, acc[nt], 0, 0, 0); }
;     }
;     const int p = 16 * w + fr; const float bias = bs[p];
;     const bf16_t* up = UV + (size_t)(r0 + p) * 512 + 64 * h + 4 * fq;
;     bf16_t* op = O + (size_t)(r0 + p) * DM + 64 * h + 4 * fq;
; #pragma unroll
;     for (int nt = 0; nt < 4; ++nt) {
;         const u32x2 uu = *(const u32x2*)(up + 16 * nt);
;         const float u0 = __uint_as_float(uu.x << 16), u1 = __uint_as_float(uu.x & 0xffff0000u), u2 = __uint_as_float(uu.y << 16), u3 = __uint_as_float(uu.y & 0xffff0000u);
;         *(u32x2*)(op + 16 * nt) = (u32x2){cvt_pk_bf16(u0 * (acc[nt][0] + bias), u1 * (acc[nt][1] + bias)), cvt_pk_bf16(u2 * (acc[nt][2] + bias), u3 * (acc[nt][3] + bias))};
;     }
;     __syncthreads();
	v_mul_f32_e32 v9, v9, v10
	v_cvt_pk_bf16_f32 v9, v9, v1
	ds_write_b16 v17, v9 offset:2176
	global_load_dword v9, v16, s[10:11] offset:36
	s_waitcnt vmcnt(0)
	v_mul_f32_e32 v8, v8, v9
	v_cvt_pk_bf16_f32 v8, v8, v1
	ds_write_b16 v17, v8 offset:2448
	global_load_dword v8, v16, s[10:11] offset:40
	s_waitcnt vmcnt(0)
	v_mul_f32_e32 v7, v7, v8
	v_cvt_pk_bf16_f32 v7, v7, v1
	ds_write_b16 v17, v7 offset:2720
	global_load_dword v7, v16, s[10:11] offset:44
	s_waitcnt vmcnt(0)
	v_mul_f32_e32 v6, v6, v7
	v_cvt_pk_bf16_f32 v6, v6, v1
	ds_write_b16 v17, v6 offset:2992
	global_load_dword v6, v16, s[10:11] offset:48
	s_waitcnt vmcnt(0)
	v_mul_f32_e32 v5, v5, v6
	v_cvt_pk_bf16_f32 v5, v5, v1
	ds_write_b16 v17, v5 offset:3264
	global_load_dword v5, v16, s[10:11] offset:52
	v_mul_u32_u24_e32 v6, 0x110, v173
	v_add3_u32 v28, 0, v162, v6
	s_waitcnt vmcnt(0)
	v_mul_f32_e32 v4, v4, v5
	v_cvt_pk_bf16_f32 v4, v4, v1
	ds_write_b16 v17, v4 offset:3536
	global_load_dword v4, v16, s[10:11] offset:56
	s_waitcnt vmcnt(0)
	v_mul_f32_e32 v3, v3, v4
	v_cvt_pk_bf16_f32 v3, v3, v1
	global_load_dword v2, v16, s[10:11] offset:60
	ds_write_b16 v17, v3 offset:3808
	s_waitcnt vmcnt(0)
	v_mul_f32_e32 v0, v0, v2
	v_lshlrev_b64 v[2:3], 8, v[160:161]
	v_lshl_add_u64 v[2:3], s[8:9], 0, v[2:3]
	v_lshl_add_u64 v[26:27], v[2:3], 0, v[162:163]
	v_cvt_pk_bf16_f32 v0, v0, v1
	ds_write_b16 v17, v0 offset:4080
	s_waitcnt lgkmcnt(0)
	s_barrier
	global_load_dwordx4 v[2:5], v[26:27], off
	ds_read_b128 v[6:9], v28
	ds_read_b128 v[22:25], v28 offset:64
	ds_read_b128 v[10:13], v28 offset:4352
	ds_read_b128 v[14:17], v28 offset:8704
	ds_read_b128 v[18:21], v28 offset:13056
	v_lshlrev_b32_e32 v0, 3, v177
	s_waitcnt vmcnt(0) lgkmcnt(4)
	v_mfma_f32_16x16x32_bf16 v[6:9], v[6:9], v[2:5], 0
	s_waitcnt lgkmcnt(2)
	v_mfma_f32_16x16x32_bf16 v[10:13], v[10:13], v[2:5], 0
	s_waitcnt lgkmcnt(1)
	v_mfma_f32_16x16x32_bf16 v[14:17], v[14:17], v[2:5], 0
	s_waitcnt lgkmcnt(0)
	v_mfma_f32_16x16x32_bf16 v[2:5], v[18:21], v[2:5], 0
	global_load_dwordx4 v[18:21], v[26:27], off offset:64
	s_waitcnt vmcnt(0)
	v_mfma_f32_16x16x32_bf16 v[6:9], v[22:25], v[18:21], v[6:9]
	ds_read_b128 v[22:25], v28 offset:4416
	s_waitcnt lgkmcnt(0)
	v_mfma_f32_16x16x32_bf16 v[10:13], v[22:25], v[18:21], v[10:13]
	ds_read_b128 v[22:25], v28 offset:8768
	s_waitcnt lgkmcnt(0)
	v_mfma_f32_16x16x32_bf16 v[14:17], v[22:25], v[18:21], v[14:17]
	ds_read_b128 v[22:25], v28 offset:13120
	s_waitcnt lgkmcnt(0)
	v_mfma_f32_16x16x32_bf16 v[2:5], v[22:25], v[18:21], v[2:5]
	global_load_dwordx4 v[18:21], v[26:27], off offset:128
	ds_read_b128 v[22:25], v28 offset:128
	s_waitcnt vmcnt(0) lgkmcnt(0)
	v_mfma_f32_16x16x32_bf16 v[6:9], v[22:25], v[18:21], v[6:9]
	ds_read_b128 v[22:25], v28 offset:4480
	s_waitcnt lgkmcnt(0)
	v_mfma_f32_16x16x32_bf16 v[10:13], v[22:25], v[18:21], v[10:13]
	ds_read_b128 v[22:25], v28 offset:8832
	s_waitcnt lgkmcnt(0)
	v_mfma_f32_16x16x32_bf16 v[22:25], v[22:25], v[18:21], v[14:17]
	s_nop 2
	ds_read_b128 v[14:17], v28 offset:13184
	s_waitcnt lgkmcnt(0)
	v_mfma_f32_16x16x32_bf16 v[2:5], v[14:17], v[18:21], v[2:5]
	global_load_dwordx4 v[18:21], v[26:27], off offset:192
	ds_read_b128 v[14:17], v28 offset:192
	s_waitcnt vmcnt(0) lgkmcnt(0)
	v_mfma_f32_16x16x32_bf16 v[14:17], v[14:17], v[18:21], v[6:9]
	s_nop 2
	ds_read_b128 v[6:9], v28 offset:4544
	s_waitcnt lgkmcnt(0)
	v_mfma_f32_16x16x32_bf16 v[10:13], v[6:9], v[18:21], v[10:13]
	ds_read_b128 v[6:9], v28 offset:8896
	s_waitcnt lgkmcnt(0)
	v_mfma_f32_16x16x32_bf16 v[6:9], v[6:9], v[18:21], v[22:25]
	s_nop 2
	ds_read_b128 v[22:25], v28 offset:13248
	s_waitcnt lgkmcnt(0)
	v_mfma_f32_16x16x32_bf16 v[2:5], v[22:25], v[18:21], v[2:5]
	v_lshl_add_u64 v[18:19], v[160:161], 2, s[0:1]
	global_load_dword v22, v[18:19], off
	v_add_u32_e32 v18, s3, v160
	v_ashrrev_i32_e32 v19, 31, v18
	v_lshlrev_b64 v[20:21], 10, v[18:19]
	v_lshl_add_u64 v[20:21], s[20:21], 0, v[20:21]
	v_lshl_add_u64 v[20:21], v[20:21], 0, s[16:17]
	v_lshl_add_u64 v[20:21], v[20:21], 0, v[0:1]
	global_load_dwordx2 v[24:25], v[20:21], off
	v_readlane_b32 s0, v252, 55
	v_lshlrev_b64 v[18:19], 11, v[18:19]
	v_readlane_b32 s1, v252, 56
	s_waitcnt vmcnt(1)
	v_add_f32_e32 v14, v14, v22
	v_lshl_add_u64 v[18:19], s[0:1], 0, v[18:19]
	v_lshl_add_u64 v[18:19], v[18:19], 0, s[16:17]
	v_lshl_add_u64 v[18:19], v[18:19], 0, v[0:1]
	v_add_f32_e32 v10, v10, v22
	v_add_f32_e32 v6, v6, v22
	v_add_f32_e32 v2, v22, v2
	s_waitcnt vmcnt(0)
	v_lshlrev_b32_e32 v0, 16, v24
	v_and_b32_e32 v23, 0xffff0000, v24
	v_mul_f32_e32 v0, v14, v0
	v_add_f32_e32 v14, v15, v22
	v_lshlrev_b32_e32 v24, 16, v25
	v_and_b32_e32 v25, 0xffff0000, v25
	v_mul_f32_e32 v14, v14, v23
	v_add_f32_e32 v15, v17, v22
	v_cvt_pk_bf16_f32 v14, v0, v14
	v_add_f32_e32 v0, v16, v22
	v_mul_f32_e32 v15, v15, v25
	v_mul_f32_e32 v0, v0, v24
	v_cvt_pk_bf16_f32 v15, v0, v15
	global_store_dwordx2 v[18:19], v[14:15], off
	global_load_dwordx2 v[14:15], v[20:21], off offset:32
	s_mov_b64 s[0:1], 0
	s_waitcnt vmcnt(0)
	v_lshlrev_b32_e32 v0, 16, v14
	v_and_b32_e32 v14, 0xffff0000, v14
	v_mul_f32_e32 v0, v10, v0
	v_add_f32_e32 v10, v11, v22
	v_lshlrev_b32_e32 v16, 16, v15
	v_and_b32_e32 v15, 0xffff0000, v15
	v_mul_f32_e32 v10, v10, v14
	v_add_f32_e32 v11, v13, v22
	v_cvt_pk_bf16_f32 v10, v0, v10
	v_add_f32_e32 v0, v12, v22
	v_mul_f32_e32 v11, v11, v15
	v_mul_f32_e32 v0, v0, v16
	v_cvt_pk_bf16_f32 v11, v0, v11
	global_store_dwordx2 v[18:19], v[10:11], off offset:32
	global_load_dwordx2 v[10:11], v[20:21], off offset:64
	s_waitcnt vmcnt(0)
	v_lshlrev_b32_e32 v0, 16, v10
	v_and_b32_e32 v10, 0xffff0000, v10
	v_mul_f32_e32 v0, v6, v0
	v_add_f32_e32 v6, v7, v22
	v_lshlrev_b32_e32 v12, 16, v11
	v_and_b32_e32 v11, 0xffff0000, v11
	v_mul_f32_e32 v6, v6, v10
	v_add_f32_e32 v7, v9, v22
	v_cvt_pk_bf16_f32 v6, v0, v6
	v_add_f32_e32 v0, v8, v22
	v_mul_f32_e32 v7, v7, v11
	v_mul_f32_e32 v0, v0, v12
	v_cvt_pk_bf16_f32 v7, v0, v7
	global_store_dwordx2 v[18:19], v[6:7], off offset:64
	global_load_dwordx2 v[6:7], v[20:21], off offset:96
	s_waitcnt vmcnt(0)
	v_lshlrev_b32_e32 v0, 16, v6
	v_and_b32_e32 v6, 0xffff0000, v6
	v_mul_f32_e32 v0, v2, v0
	v_add_f32_e32 v2, v22, v3
	v_lshlrev_b32_e32 v8, 16, v7
	v_and_b32_e32 v7, 0xffff0000, v7
	v_mul_f32_e32 v2, v2, v6
	v_add_f32_e32 v3, v22, v5
	v_cvt_pk_bf16_f32 v2, v0, v2
	v_add_f32_e32 v0, v22, v4
	v_mul_f32_e32 v3, v3, v7
	v_mul_f32_e32 v0, v0, v8
	v_cvt_pk_bf16_f32 v3, v0, v3
	global_store_dwordx2 v[18:19], v[2:3], off offset:96
	s_barrier

; template <int NMAP, int VD, bool SWA> ...
;     ...
;     { const bf16_t* qr = Qp + (size_t)(16 * w + fr) * qpitch + fq * 8;
; #pragma unroll
;       for (int mp = 0; mp < NMAP; ++mp)
; #pragma unroll
;           for (int ks = 0; ks < 2; ++ks) qf[mp][ks] = *(const bf16x8*)(qr + mp * 64 + ks * 32); }
;     f32x4 oacc[NMAP][NET], negm[NMAP]; float mrun[NMAP], lsum[NMAP];
; #pragma unroll
;     for (int mp = 0; mp < NMAP; ++mp) { mrun[mp] = 0.f; lsum[mp] = 0.f; negm[mp] = (f32x4){0.f, 0.f, 0.f, 0.f};
; #pragma unroll
;         for (int et = 0; et < NET; ++et) oacc[mp][et] = (f32x4){0.f, 0.f, 0.f, 0.f}; }
;     const int ntiles = n0 + (t1hi - t1lo);
;     u32x4 kreg[NKC], vreg[NVC];
;     ...
;     ATT_LOAD(ATT_TILE(0));
;     ATT_STORE(0);
;     if (ntiles > 1) ATT_LOAD(ATT_TILE(1));
;     __syncthreads();
; __device__ __forceinline__ void mix_phase(const Args& a, LAS unsigned char* lds, int l, int tid_in, int G) {
;     ...
;             const bool is_swa = (u >= e0 && u < e1) || (u >= e2);
;             const bool is_ctx = (u >= e1);
;             int b, hh, qb, row0;
;             if (u < e0) {
;                 const int v = u, x = v & 7, slot = (v >> 3) & 31, rnd = v >> 8, P = x * 4 + rnd * 2 + (slot >> 4);
;                 b = P >> 2; hh = P & 3; qb = slot & 15; row0 = b * SEQ + 128 * qb; }
;             else if (u < e1) { const int v = u - e0, x = v & 7, slot = (v >> 3) & 31, P = x * 2 + (slot >> 4); b = P >> 1; hh = P & 1; qb = slot & 15; row0 = b * SEQ + 128 * qb; }
;             else if (u < e2) { const int v = u - e1; b = v >> 3; hh = (v >> 1) & 3; qb = v & 1; row0 = T_LAT + b * CTXL + 128 * qb; }
;             else { const int v = u - e2; b = v >> 2; hh = (v >> 1) & 1; qb = v & 1; row0 = T_LAT + b * CTXL + 128 * qb; }
;             if (!is_swa) {
;                 attn_unit<2, 128, false>(lds, QB + (size_t)row0 * 512 + hh * 128, 512, KB + (size_t)(b * 4 + hh) * NKEY * 128, VBt + (size_t)(b * 4 + hh) * NKEY * 128,
;                                          is_ctx ? 4 : 36, 0, 0, 0, 0.f, lam, gsub, post_scale, O + (size_t)row0 * DM + 256 + hh * 128, tid);
.LBB0_121:
	s_and_b32 s0, s22, 0xffffff00
	s_cmpk_eq_i32 s0, 0x200
	s_cselect_b64 s[0:1], -1, 0
	s_cmp_ge_i32 s22, s13
	s_cselect_b64 s[8:9], -1, 0
	s_or_b64 s[10:11], s[8:9], s[0:1]
	s_cmpk_gt_i32 s22, 0x2ff
	s_mov_b64 s[8:9], -1
	s_cselect_b64 s[0:1], -1, 0
	s_and_b64 vcc, exec, s[10:11]
	v_ashrrev_i32_e32 v178, 31, v176
	v_lshlrev_b32_e32 v175, 2, v177
	s_cbranch_vccnz .LBB0_139
	s_ashr_i32 s21, s20, 31
	s_lshl_b64 s[8:9], s[20:21], 10
	v_readlane_b32 s3, v252, 43
	s_add_u32 s3, s3, s8
	v_readlane_b32 s8, v252, 44
	s_addc_u32 s8, s8, s9
	s_lshl_b32 s25, s16, 7
	s_lshl_b32 s9, s16, 8
	s_waitcnt lgkmcnt(0)
	v_add_u32_e32 v22, 0x200, v176
	s_add_u32 s28, s3, s9
	v_lshrrev_b32_e32 v0, 28, v178
	v_ashrrev_i32_e32 v23, 31, v22
	s_addc_u32 s29, s8, 0
	s_lshl_b32 s14, s24, 2
	v_add_u32_e32 v0, v176, v0
	v_lshrrev_b32_e32 v23, 28, v23
	s_add_i32 s14, s14, s16
	v_ashrrev_i32_e32 v34, 4, v0
	v_add_u32_e32 v23, v22, v23
	s_mul_i32 s8, s14, 0x90000
	v_readlane_b32 s9, v252, 47
	v_and_b32_e32 v0, -16, v0
	v_ashrrev_i32_e32 v35, 31, v34
	v_ashrrev_i32_e32 v36, 4, v23
	v_and_b32_e32 v23, -16, v23
	s_mul_hi_i32 s3, s14, 0x90000
	s_add_u32 s10, s9, s8
	v_readlane_b32 s9, v252, 48
	v_sub_u32_e32 v0, v176, v0
	v_lshlrev_b64 v[58:59], 8, v[34:35]
	v_sub_u32_e32 v35, v22, v23
	s_addc_u32 s11, s9, s3
	v_readlane_b32 s9, v252, 49
	v_ashrrev_i32_e32 v161, 31, v160
	v_lshlrev_b32_e32 v20, 3, v0
	v_ashrrev_i32_e32 v37, 31, v36
	v_lshlrev_b32_e32 v24, 3, v35
	s_add_u32 s8, s9, s8
	v_readlane_b32 s9, v252, 50
	v_lshlrev_b64 v[2:3], 10, v[160:161]
	v_ashrrev_i32_e32 v21, 31, v20
	v_lshlrev_b64 v[94:95], 8, v[36:37]
	v_ashrrev_i32_e32 v25, 31, v24
	s_addc_u32 s9, s9, s3
	v_lshl_add_u64 v[2:3], s[28:29], 0, v[2:3]
	v_mov_b32_e32 v163, v1
	v_lshl_add_u64 v[18:19], s[10:11], 0, v[58:59]
	v_lshlrev_b64 v[60:61], 1, v[20:21]
	v_lshl_add_u64 v[22:23], s[10:11], 0, v[94:95]
	v_lshlrev_b64 v[96:97], 1, v[24:25]
	v_lshl_add_u64 v[2:3], v[2:3], 0, v[162:163]
	v_lshl_add_u64 v[18:19], v[18:19], 0, v[60:61]
	v_lshl_add_u64 v[22:23], v[22:23], 0, v[96:97]
	v_lshl_add_u64 v[26:27], s[8:9], 0, v[58:59]
	global_load_dwordx4 v[14:17], v[2:3], off
	global_load_dwordx4 v[10:13], v[2:3], off offset:64
	global_load_dwordx4 v[6:9], v[2:3], off offset:128
	s_nop 0
	global_load_dwordx4 v[2:5], v[2:3], off offset:192
	v_lshl_add_u64 v[26:27], v[26:27], 0, v[60:61]
	global_load_dwordx4 v[18:21], v[18:19], off
	v_lshl_add_u64 v[30:31], s[8:9], 0, v[94:95]
	global_load_dwordx4 v[22:25], v[22:23], off
	v_lshl_add_u64 v[30:31], v[30:31], 0, v[96:97]
	global_load_dwordx4 v[26:29], v[26:27], off
	s_movk_i32 s15, 0x120
	global_load_dwordx4 v[30:33], v[30:31], off
	v_mul_lo_u32 v208, v34, s15
	v_lshlrev_b32_e32 v209, 4, v0
	v_mul_lo_u32 v210, v36, s15
	v_lshlrev_b32_e32 v211, 4, v35
	v_add3_u32 v34, 0, v208, v209
	v_add3_u32 v35, 0, v210, v211
	s_mov_b64 s[34:35], 0x4000
	v_lshlrev_b32_e32 v36, 2, v176
	v_and_b32_e32 v56, 12, v36
	v_mbcnt_hi_u32_b32 v36, -1, v190
	v_and_b32_e32 v38, 64, v36
	v_xor_b32_e32 v37, 16, v36
	v_add_u32_e32 v38, 64, v38
	v_cmp_lt_i32_e32 vcc, v37, v38
	v_mul_u32_u24_e32 v182, 0x120, v173
	v_add3_u32 v57, 0, v162, v182
	v_cndmask_b32_e32 v37, v36, v37, vcc
	v_lshlrev_b32_e32 v179, 2, v37
	v_xor_b32_e32 v37, 32, v36
	v_cmp_lt_i32_e32 vcc, v37, v38
	v_readlane_b32 s28, v254, 39
	v_readlane_b32 s29, v254, 40
	v_cndmask_b32_e32 v36, v36, v37, vcc
	v_lshlrev_b32_e32 v180, 2, v36
	v_lshlrev_b32_e32 v163, 2, v177
	v_bfe_u32 v0, v176, 2, 2
	s_mov_b32 s26, s28
	v_readlane_b32 s28, v254, 43
	v_or_b32_e32 v0, v163, v0
	v_readlane_b32 s29, v254, 44
	v_lshlrev_b32_e32 v107, 3, v177
	s_mov_b32 s3, 1
	v_mul_u32_u24_e32 v0, 0x120, v0
	s_waitcnt vmcnt(3)
	ds_write_b128 v34, v[18:21]
	s_waitcnt vmcnt(2)
	ds_write_b128 v35, v[22:25]
	s_waitcnt vmcnt(1)
	ds_write_b128 v34, v[26:29] offset:18432
	s_waitcnt vmcnt(0)
	ds_write_b128 v35, v[30:33] offset:18432
	v_lshl_add_u64 v[26:27], v[58:59], 0, s[34:35]
	v_lshl_add_u64 v[18:19], s[10:11], 0, v[26:27]
	v_lshl_add_u64 v[30:31], v[94:95], 0, s[34:35]
	v_lshl_add_u64 v[18:19], v[18:19], 0, v[60:61]
	v_lshl_add_u64 v[22:23], s[10:11], 0, v[30:31]
	global_load_dwordx4 v[18:21], v[18:19], off
	v_lshl_add_u64 v[22:23], v[22:23], 0, v[96:97]
	v_lshl_add_u64 v[26:27], s[8:9], 0, v[26:27]
	global_load_dwordx4 v[22:25], v[22:23], off
	v_lshl_add_u64 v[26:27], v[26:27], 0, v[60:61]
	v_lshl_add_u64 v[30:31], s[8:9], 0, v[30:31]
	global_load_dwordx4 v[26:29], v[26:27], off
	v_lshl_add_u64 v[30:31], v[30:31], 0, v[96:97]
	global_load_dwordx4 v[30:33], v[30:31], off
	s_mov_b64 s[34:35], 0x8000
	s_waitcnt lgkmcnt(0)
	s_barrier
; #define LAS __attribute__((address_space(3)))
; template <int NMAP, int VD, bool SWA> ...
;     ...
;     for (int i = 0; i < ntiles; ++i) {
;         const int t = ATT_TILE(i);
;         if (i + 1 < ntiles) { ATT_STORE((i + 1) & 1); if (i + 2 < ntiles) ATT_LOAD(ATT_TILE(i + 2)); }
;         const LAS bf16_t* kS = (const LAS bf16_t*)(lds + (i & 1) * BUFB);
;         const LAS bf16_t* vS = (const LAS bf16_t*)(lds + (i & 1) * BUFB + KBYTES);
;         bf16x8 pf[NMAP][2];
;         f32x4 sacc[NMAP][4];
; #pragma unroll
;         for (int mp = 0; mp < NMAP; ++mp) {
;             bf16x8 kf[4][2];
; #pragma unroll
;             for (int kt = 0; kt < 4; ++kt)
; #pragma unroll
;                 for (int ks = 0; ks < 2; ++ks) kf[kt][ks] = *(const LAS bf16x8*)(kS + (16 * kt + fr) * KP + mp * KMS + ks * 32 + fq * 8);
;             __builtin_amdgcn_sched_barrier(0);
; #pragma unroll
;             for (int kt = 0; kt < 4; ++kt) sacc[mp][kt] = __builtin_amdgcn_mfma_f32_16x16x32_bf16(kf[kt][0], qf[mp][0], negm[mp], 0, 0, 0);
; #pragma unroll
;             for (int kt = 0; kt < 4; ++kt) sacc[mp][kt] = __builtin_amdgcn_mfma_f32_16x16x32_bf16(kf[kt][1], qf[mp][1], sacc[mp][kt], 0, 0, 0);
;         }
;         bf16x8 va[4];
;     ...
; #pragma unroll
;         for (int i2 = 0; i2 < 4; ++i2) ATT_LDV(va[i2], i2);
;         if (SWA && t >= 4) {
;             const int dq = qp0 + 16 * w + fr - (64 * (t - 4) + 4 * fq);
; #pragma unroll
;             for (int kt = 0; kt < 4; ++kt)
; #pragma unroll
;                 for (int r = 0; r < 4; ++r) { const int d = dq - 16 * kt - r; if (d > 128 || d < -128) {
; #pragma unroll
;                     for (int mp = 0; mp < NMAP; ++mp) sacc[mp][kt][r] = -INFINITY; } }
;         }
;         float mx[NMAP];
; #pragma unroll
;         for (int mp = 0; mp < NMAP; ++mp) {
;             float v = fmax2(fmax2(sacc[mp][0][0], sacc[mp][0][1]), fmax2(sacc[mp][0][2], sacc[mp][0][3]));
; #pragma unroll
;             for (int kt = 1; kt < 4; ++kt) v = fmax2(v, fmax2(fmax2(sacc[mp][kt][0], sacc[mp][kt][1]), fmax2(sacc[mp][kt][2], sacc[mp][kt][3])));
;             mx[mp] = v;
;         }
; #pragma unroll
;         for (int mp = 0; mp < NMAP; ++mp) mx[mp] = fmax2(mx[mp], __shfl_xor(mx[mp], 16));
; #pragma unroll
;         for (int mp = 0; mp < NMAP; ++mp) mx[mp] = fmax2(mx[mp], __shfl_xor(mx[mp], 32));
; #pragma unroll
;         for (int mp = 0; mp < NMAP; ++mp) {
	s_waitcnt vmcnt(3)
	ds_write_b128 v34, v[18:21] offset:36864
	s_waitcnt vmcnt(2)
	ds_write_b128 v35, v[22:25] offset:36864
	s_waitcnt vmcnt(1)
	ds_write_b128 v34, v[26:29] offset:55296
	s_waitcnt vmcnt(0)
	ds_write_b128 v35, v[30:33] offset:55296
	v_lshl_add_u64 v[18:19], v[58:59], 0, s[34:35]
	v_lshl_add_u64 v[20:21], s[10:11], 0, v[18:19]
	v_lshl_add_u64 v[18:19], s[8:9], 0, v[18:19]
	v_lshl_add_u64 v[20:21], v[20:21], 0, v[60:61]
	v_lshl_add_u64 v[18:19], v[18:19], 0, v[60:61]
	global_load_dwordx4 v[86:89], v[20:21], off
	global_load_dwordx4 v[98:101], v[18:19], off
	v_lshl_add_u64 v[20:21], v[94:95], 0, s[34:35]
	v_lshl_add_u64 v[22:23], s[10:11], 0, v[20:21]
	v_lshl_add_u64 v[18:19], s[8:9], 0, v[20:21]
	v_lshl_add_u64 v[22:23], v[22:23], 0, v[96:97]
	v_lshl_add_u64 v[18:19], v[18:19], 0, v[96:97]
	global_load_dwordx4 v[90:93], v[22:23], off
	global_load_dwordx4 v[102:105], v[18:19], off
	ds_read_b128 v[18:21], v57
	ds_read_b128 v[22:25], v57 offset:64
	ds_read_b128 v[26:29], v57 offset:4608
	ds_read_b128 v[30:33], v57 offset:4672
	ds_read_b128 v[34:37], v57 offset:9216
	ds_read_b128 v[38:41], v57 offset:9280
	ds_read_b128 v[42:45], v57 offset:13824
	ds_read_b128 v[46:49], v57 offset:13888
	s_waitcnt lgkmcnt(7)
	v_mfma_f32_16x16x32_bf16 v[18:21], v[18:21], v[14:17], 0
	s_waitcnt lgkmcnt(5)
	v_mfma_f32_16x16x32_bf16 v[26:29], v[26:29], v[14:17], 0
	s_waitcnt lgkmcnt(3)
	v_mfma_f32_16x16x32_bf16 v[34:37], v[34:37], v[14:17], 0
	s_waitcnt lgkmcnt(1)
	v_mfma_f32_16x16x32_bf16 v[42:45], v[42:45], v[14:17], 0
	v_mfma_f32_16x16x32_bf16 v[18:21], v[22:25], v[10:13], v[18:21]
	v_mfma_f32_16x16x32_bf16 v[24:27], v[30:33], v[10:13], v[26:29]
	v_mfma_f32_16x16x32_bf16 v[28:31], v[38:41], v[10:13], v[34:37]
	s_waitcnt lgkmcnt(0)
	v_mfma_f32_16x16x32_bf16 v[32:35], v[46:49], v[10:13], v[42:45]
	s_nop 0
	ds_read_b128 v[36:39], v57 offset:128
	s_nop 0
	ds_read_b128 v[40:43], v57 offset:192
	ds_read_b128 v[44:47], v57 offset:4736
	ds_read_b128 v[48:51], v57 offset:4800
	ds_read_b128 v[52:55], v57 offset:9344
	ds_read_b128 v[62:65], v57 offset:9408
	ds_read_b128 v[66:69], v57 offset:13952
	ds_read_b128 v[70:73], v57 offset:14016
	v_lshlrev_b32_e32 v181, 1, v56
	v_med3_f32 v23, v18, v19, s27
	v_med3_f32 v56, v20, v21, s27
	s_waitcnt lgkmcnt(7)
	v_mfma_f32_16x16x32_bf16 v[36:39], v[36:39], v[6:9], 0
	v_med3_f32 v23, v23, v56, s27
	v_med3_f32 v56, v24, v25, s27
	v_med3_f32 v57, v26, v27, s27
	v_med3_f32 v56, v56, v57, s27
	s_waitcnt lgkmcnt(5)
	v_mfma_f32_16x16x32_bf16 v[44:47], v[44:47], v[6:9], 0
	v_med3_f32 v23, v23, v56, s27
	v_med3_f32 v56, v28, v29, s27
	v_med3_f32 v57, v30, v31, s27
	v_med3_f32 v56, v56, v57, s27
	v_med3_f32 v23, v23, v56, s27
	v_med3_f32 v56, v32, v33, s27
	v_mfma_f32_16x16x32_bf16 v[36:39], v[40:43], v[2:5], v[36:39]
	v_med3_f32 v40, v34, v35, s27
	v_med3_f32 v40, v56, v40, s27
	v_med3_f32 v23, v23, v40, s27
	s_waitcnt lgkmcnt(3)
	v_mfma_f32_16x16x32_bf16 v[52:55], v[52:55], v[6:9], 0
	v_add3_u32 v22, 0, v0, v181
	v_mad_i64_i32 v[58:59], s[8:9], s14, v192, v[58:59]
	v_mfma_f32_16x16x32_bf16 v[40:43], v[48:51], v[2:5], v[44:47]
	v_lshl_add_u64 v[58:59], v[58:59], 0, v[60:61]
	s_and_b64 s[8:9], s[0:1], exec
	s_cselect_b32 s10, 1, 33
	s_waitcnt lgkmcnt(1)
	v_mfma_f32_16x16x32_bf16 v[66:69], v[66:69], v[6:9], 0
	v_med3_f32 v44, v36, v37, s27
	v_med3_f32 v45, v38, v39, s27
	v_med3_f32 v56, v44, v45, s27
	v_mfma_f32_16x16x32_bf16 v[44:47], v[62:65], v[2:5], v[52:55]
	v_med3_f32 v48, v40, v41, s27
	v_med3_f32 v49, v42, v43, s27
	s_lshl_b32 s11, s10, 14
	v_med3_f32 v52, v48, v49, s27
	s_waitcnt lgkmcnt(0)
	v_mfma_f32_16x16x32_bf16 v[48:51], v[70:73], v[2:5], v[66:69]
	s_nop 1
	v_med3_f32 v53, v44, v45, s27
	v_med3_f32 v54, v46, v47, s27
	v_med3_f32 v52, v56, v52, s27
	v_med3_f32 v53, v53, v54, s27
	v_med3_f32 v52, v52, v53, s27
	s_nop 0
	v_med3_f32 v53, v48, v49, s27
	v_med3_f32 v54, v50, v51, s27
	v_med3_f32 v53, v53, v54, s27
	v_med3_f32 v54, v52, v53, s27
	ds_bpermute_b32 v55, v179, v23
	ds_bpermute_b32 v56, v179, v54
	ds_read_b64_tr_b16 v[52:53], v22 offset:18432
	ds_read_b64_tr_b16 v[62:63], v22 offset:18464
	ds_read_b64_tr_b16 v[66:67], v22 offset:18496
	ds_read_b64_tr_b16 v[70:71], v22 offset:18528
	s_waitcnt lgkmcnt(5)
	v_med3_f32 v23, v23, v55, s27
	s_waitcnt lgkmcnt(4)
	v_med3_f32 v56, v54, v56, s27
	ds_bpermute_b32 v57, v180, v23
	ds_bpermute_b32 v74, v180, v56
	ds_read_b64_tr_b16 v[54:55], v22 offset:23040
	ds_read_b64_tr_b16 v[64:65], v22 offset:23072
	ds_read_b64_tr_b16 v[68:69], v22 offset:23104
	ds_read_b64_tr_b16 v[72:73], v22 offset:23136
	s_waitcnt lgkmcnt(5)
	v_med3_f32 v23, v23, v57, s27
	s_waitcnt lgkmcnt(4)
	v_med3_f32 v109, v56, v74, s27
	v_sub_f32_e32 v35, v35, v23
	v_sub_f32_e32 v34, v34, v23
	v_sub_f32_e32 v33, v33, v23
	v_sub_f32_e32 v32, v32, v23
	v_sub_f32_e32 v31, v31, v23
	v_sub_f32_e32 v30, v30, v23
	v_sub_f32_e32 v29, v29, v23
	v_sub_f32_e32 v28, v28, v23
	v_sub_f32_e32 v27, v27, v23
	v_sub_f32_e32 v26, v26, v23
	v_sub_f32_e32 v25, v25, v23
	v_sub_f32_e32 v24, v24, v23
	v_sub_f32_e32 v21, v21, v23
	v_sub_f32_e32 v20, v20, v23
	v_sub_f32_e32 v19, v19, v23
	v_sub_f32_e32 v18, v18, v23
	v_exp_f32_e32 v111, v28
	v_exp_f32_e32 v156, v29
	v_exp_f32_e32 v157, v30
	v_exp_f32_e32 v164, v31
	v_exp_f32_e32 v165, v32
	v_exp_f32_e32 v166, v33
	v_exp_f32_e32 v167, v34
	v_exp_f32_e32 v183, v35
	v_sub_f32_e32 v28, v43, v109
	v_sub_f32_e32 v29, v42, v109
	v_sub_f32_e32 v30, v41, v109
	v_sub_f32_e32 v31, v40, v109
	v_sub_f32_e32 v32, v39, v109
	v_sub_f32_e32 v33, v38, v109
	v_sub_f32_e32 v34, v37, v109
	v_sub_f32_e32 v35, v36, v109
	v_exp_f32_e32 v56, v18
	v_exp_f32_e32 v57, v19
	v_exp_f32_e32 v74, v20
	v_exp_f32_e32 v75, v21
	v_exp_f32_e32 v76, v24
	v_exp_f32_e32 v106, v25
	v_exp_f32_e32 v108, v26
	v_exp_f32_e32 v110, v27
	v_cvt_pk_bf16_f32 v24, v56, v57
	v_cvt_pk_bf16_f32 v25, v74, v75
	v_cvt_pk_bf16_f32 v26, v76, v106
	v_cvt_pk_bf16_f32 v27, v108, v110
	v_cvt_pk_bf16_f32 v18, v111, v156
	v_cvt_pk_bf16_f32 v19, v157, v164
	v_cvt_pk_bf16_f32 v20, v165, v166
	v_cvt_pk_bf16_f32 v21, v167, v183
	v_sub_f32_e32 v77, v51, v109
	v_sub_f32_e32 v78, v50, v109
	v_sub_f32_e32 v79, v49, v109
	v_exp_f32_e32 v202, v35
	v_exp_f32_e32 v203, v34
	v_exp_f32_e32 v212, v33
	v_exp_f32_e32 v213, v32
	v_exp_f32_e32 v214, v31
	v_exp_f32_e32 v215, v30
	v_exp_f32_e32 v216, v29
	v_exp_f32_e32 v217, v28
	v_cvt_pk_bf16_f32 v28, v202, v203
	s_waitcnt lgkmcnt(3)
; __device__ __forceinline__ unsigned cvt_pk_bf16(float lo, float hi) { unsigned r; asm volatile("v_cvt_pk_bf16_f32 %0, %1, %2" : "=v"(r) : "v"(lo), "v"(hi)); return r; }
; template <int NMAP, int VD, bool SWA> ...
;     ...
;             float ps = 0.f;
; #pragma unroll
;             for (int kt = 0; kt < 4; ++kt)
; #pragma unroll
;                 for (int r = 0; r < 4; ++r) { const float p = __builtin_amdgcn_exp2f(sacc[mp][kt][r]); sacc[mp][kt][r] = p; ps += p; }
;             lsum[mp] += ps;
; #pragma unroll
;             for (int s2 = 0; s2 < 2; ++s2) {
;                 u32x4 pk; pk.x = cvt_pk_bf16(sacc[mp][2 * s2][0], sacc[mp][2 * s2][1]); pk.y = cvt_pk_bf16(sacc[mp][2 * s2][2], sacc[mp][2 * s2][3]);
;                 pk.z = cvt_pk_bf16(sacc[mp][2 * s2 + 1][0], sacc[mp][2 * s2 + 1][1]); pk.w = cvt_pk_bf16(sacc[mp][2 * s2 + 1][2], sacc[mp][2 * s2 + 1][3]);
;                 pf[mp][s2] = __builtin_bit_cast(bf16x8, pk);
;             }
;         }
; #pragma unroll
;         for (int idx = 0; idx < 2 * NET; ++idx) {
;             const int et = idx % NET, s2 = idx / NET;
;             const bf16x8 cur = va[idx & 3];
;             if (idx + 4 < 2 * NET) ATT_LDV(va[idx & 3], idx + 4);
; #pragma unroll
;             for (int mp = 0; mp < NMAP; ++mp) oacc[mp][et] = __builtin_amdgcn_mfma_f32_16x16x32_bf16(cur, pf[mp][s2], oacc[mp][et], 0, 0, 0);
;         }
;     ...
;         __syncthreads();
	v_mfma_f32_16x16x32_bf16 v[32:35], v[52:55], v[24:27], 0
	v_cvt_pk_bf16_f32 v29, v212, v213
	v_cvt_pk_bf16_f32 v30, v214, v215
	v_cvt_pk_bf16_f32 v31, v216, v217
	v_sub_f32_e32 v49, v46, v109
	v_mfma_f32_16x16x32_bf16 v[36:39], v[52:55], v[28:31], 0
	v_sub_f32_e32 v52, v48, v109
	v_sub_f32_e32 v48, v47, v109
	v_sub_f32_e32 v50, v45, v109
	v_sub_f32_e32 v44, v44, v109
	s_waitcnt lgkmcnt(2)
	v_mfma_f32_16x16x32_bf16 v[40:43], v[62:65], v[24:27], 0
	v_exp_f32_e32 v218, v44
	v_exp_f32_e32 v219, v50
	v_exp_f32_e32 v220, v49
	v_mfma_f32_16x16x32_bf16 v[44:47], v[62:65], v[28:31], 0
	v_exp_f32_e32 v221, v48
	v_exp_f32_e32 v222, v52
	v_exp_f32_e32 v223, v79
	v_exp_f32_e32 v224, v78
	v_exp_f32_e32 v225, v77
	v_cvt_pk_bf16_f32 v112, v218, v219
	v_cvt_pk_bf16_f32 v113, v220, v221
	v_cvt_pk_bf16_f32 v114, v222, v223
	v_cvt_pk_bf16_f32 v115, v224, v225
	ds_read_b64_tr_b16 v[64:65], v22 offset:23168
	ds_read_b64_tr_b16 v[62:63], v22 offset:18560
	s_waitcnt lgkmcnt(3)
	v_mfma_f32_16x16x32_bf16 v[48:51], v[66:69], v[24:27], 0
	v_mfma_f32_16x16x32_bf16 v[52:55], v[66:69], v[28:31], 0
	ds_read_b64_tr_b16 v[68:69], v22 offset:23200
	ds_read_b64_tr_b16 v[66:67], v22 offset:18592
	s_waitcnt lgkmcnt(2)
	v_mfma_f32_16x16x32_bf16 v[124:127], v[62:65], v[24:27], 0
	v_mfma_f32_16x16x32_bf16 v[128:131], v[62:65], v[28:31], 0
	ds_read_b64_tr_b16 v[62:63], v22 offset:18624
	ds_read_b64_tr_b16 v[64:65], v22 offset:23232
	s_waitcnt lgkmcnt(2)
	v_mfma_f32_16x16x32_bf16 v[132:135], v[66:69], v[24:27], 0
	v_mfma_f32_16x16x32_bf16 v[136:139], v[66:69], v[28:31], 0
	ds_read_b64_tr_b16 v[66:67], v22 offset:18656
	s_waitcnt lgkmcnt(1)
	v_mfma_f32_16x16x32_bf16 v[140:143], v[62:65], v[24:27], 0
	v_mfma_f32_16x16x32_bf16 v[144:147], v[62:65], v[28:31], 0
	ds_read_b64_tr_b16 v[68:69], v22 offset:23264
	ds_read_b64_tr_b16 v[62:63], v22 offset:27648
	v_mfma_f32_16x16x32_bf16 v[116:119], v[70:73], v[24:27], 0
	s_waitcnt lgkmcnt(1)
	v_mfma_f32_16x16x32_bf16 v[148:151], v[66:69], v[24:27], 0
	ds_read_b64_tr_b16 v[64:65], v22 offset:32256
	ds_read_b64_tr_b16 v[24:25], v22 offset:27680
	ds_read_b64_tr_b16 v[152:153], v22 offset:27712
	s_waitcnt lgkmcnt(2)
	v_mfma_f32_16x16x32_bf16 v[78:81], v[62:65], v[18:21], v[32:35]
	s_nop 2
	v_add_f32_e32 v32, 0, v56
	v_add_f32_e32 v32, v57, v32
	v_add_f32_e32 v32, v74, v32
	v_add_f32_e32 v32, v75, v32
	v_mfma_f32_16x16x32_bf16 v[120:123], v[70:73], v[28:31], 0
	v_add_f32_e32 v32, v76, v32
	v_add_f32_e32 v32, v106, v32
	v_add_f32_e32 v32, v108, v32
	v_mfma_f32_16x16x32_bf16 v[168:171], v[66:69], v[28:31], 0
	ds_read_b64_tr_b16 v[28:29], v22 offset:27744
	ds_read_b64_tr_b16 v[26:27], v22 offset:32288
	ds_read_b64_tr_b16 v[154:155], v22 offset:32320
	ds_read_b64_tr_b16 v[30:31], v22 offset:32352
	v_add_f32_e32 v32, v110, v32
	s_waitcnt lgkmcnt(2)
	v_mfma_f32_16x16x32_bf16 v[74:77], v[24:27], v[18:21], v[40:43]
	v_mfma_f32_16x16x32_bf16 v[70:73], v[24:27], v[112:115], v[44:47]
	v_add_f32_e32 v24, v111, v32
	v_add_f32_e32 v24, v156, v24
	v_add_f32_e32 v24, v157, v24
	v_add_f32_e32 v24, v164, v24
	v_add_f32_e32 v24, v165, v24
	v_add_f32_e32 v24, v166, v24
	v_mfma_f32_16x16x32_bf16 v[82:85], v[62:65], v[112:115], v[36:39]
	s_nop 2
	v_add_f32_e32 v36, v167, v24
	s_waitcnt lgkmcnt(1)
	v_mfma_f32_16x16x32_bf16 v[66:69], v[152:155], v[18:21], v[48:51]
	ds_read_b64_tr_b16 v[24:25], v22 offset:27776
	ds_read_b64_tr_b16 v[26:27], v22 offset:32384
	v_mfma_f32_16x16x32_bf16 v[62:65], v[152:155], v[112:115], v[52:55]
	s_waitcnt lgkmcnt(2)
	v_mfma_f32_16x16x32_bf16 v[54:57], v[28:31], v[18:21], v[116:119]
	ds_read_b64_tr_b16 v[32:33], v22 offset:27808
	s_nop 1
	ds_read_b64_tr_b16 v[116:117], v22 offset:27840
	ds_read_b64_tr_b16 v[152:153], v22 offset:27872
	ds_read_b64_tr_b16 v[34:35], v22 offset:32416
	ds_read_b64_tr_b16 v[118:119], v22 offset:32448
	ds_read_b64_tr_b16 v[154:155], v22 offset:32480
	v_add_f32_e32 v22, v183, v36
	v_pk_add_f32 v[166:167], v[22:23], 0 op_sel_hi:[1,0]
	v_add_f32_e32 v22, 0, v202
	v_add_f32_e32 v22, v203, v22
	v_add_f32_e32 v22, v212, v22
	v_add_f32_e32 v22, v213, v22
	v_add_f32_e32 v22, v214, v22
	v_add_f32_e32 v22, v215, v22
	v_add_f32_e32 v22, v216, v22
	v_add_f32_e32 v22, v217, v22
	v_add_f32_e32 v22, v218, v22
	v_add_f32_e32 v22, v219, v22
	v_add_f32_e32 v22, v220, v22
	v_add_f32_e32 v22, v221, v22
	v_add_f32_e32 v22, v222, v22
	v_add_f32_e32 v22, v223, v22
	v_add_f32_e32 v108, v224, v22
	v_mfma_f32_16x16x32_bf16 v[50:53], v[28:31], v[112:115], v[120:123]
	v_add_f32_e32 v108, v225, v108
	v_pk_add_f32 v[164:165], v[108:109], 0 op_sel_hi:[1,0]
	v_xor_b32_e32 v106, 0x80000000, v167
	s_waitcnt lgkmcnt(6)
	v_mfma_f32_16x16x32_bf16 v[46:49], v[24:27], v[18:21], v[124:127]
	v_xor_b32_e32 v110, 0x80000000, v165
	v_lshlrev_b32_e32 v183, 1, v107
	v_mov_b32_e32 v111, v110
	v_mfma_f32_16x16x32_bf16 v[42:45], v[24:27], v[112:115], v[128:131]
	v_mov_b32_e32 v107, v106
	v_mov_b32_e32 v108, v106
	v_mov_b32_e32 v109, v106
	s_waitcnt lgkmcnt(2)
	v_mfma_f32_16x16x32_bf16 v[38:41], v[32:35], v[18:21], v[132:135]
	s_waitcnt lgkmcnt(0)
	s_barrier
	v_mfma_f32_16x16x32_bf16 v[34:37], v[32:35], v[112:115], v[136:139]
	v_mfma_f32_16x16x32_bf16 v[30:33], v[116:119], v[18:21], v[140:143]
	v_mfma_f32_16x16x32_bf16 v[26:29], v[116:119], v[112:115], v[144:147]
	v_mfma_f32_16x16x32_bf16 v[22:25], v[152:155], v[18:21], v[148:151]
	v_mfma_f32_16x16x32_bf16 v[18:21], v[152:155], v[112:115], v[168:171]
	v_mov_b32_e32 v112, v110
	v_mov_b32_e32 v113, v110
	s_nop 0
	v_lshl_add_u64 v[168:169], s[4:5], 0, v[58:59]
	v_mad_i64_i32 v[58:59], s[8:9], s14, v192, v[94:95]
	v_lshl_add_u64 v[58:59], v[58:59], 0, v[96:97]
	v_lshl_add_u64 v[170:171], s[4:5], 0, v[58:59]
	s_mov_b64 s[8:9], 0
	v_subrev_u32_e32 v236, s4, v168
	v_subrev_u32_e32 v237, s4, v170
	v_add_u32_e32 v238, 0x1200000, v236
	v_add_u32_e32 v239, 0x1200000, v237
	s_add_u32 s34, s4, 0x1810c000
	s_addc_u32 s35, s5, 0
	s_branch .LBB0_125

; template <int NMAP, int VD, bool SWA> ...
;     ...
;     { const bf16_t* qr = Qp + (size_t)(16 * w + fr) * qpitch + fq * 8;
; #pragma unroll
;       for (int mp = 0; mp < NMAP; ++mp)
; #pragma unroll
;           for (int ks = 0; ks < 2; ++ks) qf[mp][ks] = *(const bf16x8*)(qr + mp * 64 + ks * 32); }
;     f32x4 oacc[NMAP][NET], negm[NMAP]; float mrun[NMAP], lsum[NMAP];
; #pragma unroll
;     for (int mp = 0; mp < NMAP; ++mp) { mrun[mp] = 0.f; lsum[mp] = 0.f; negm[mp] = (f32x4){0.f, 0.f, 0.f, 0.f};
; #pragma unroll
;         for (int et = 0; et < NET; ++et) oacc[mp][et] = (f32x4){0.f, 0.f, 0.f, 0.f}; }
;     const int ntiles = n0 + (t1hi - t1lo);
;     u32x4 kreg[NKC], vreg[NVC];
;     ...
;     ATT_LOAD(ATT_TILE(0));
;     ATT_STORE(0);
; __device__ __forceinline__ void mix_phase(const Args& a, LAS unsigned char* lds, int l, int tid_in, int G) {
;     ...
;             } else {
;                 const int kv = hh;
;                 int lo = 4 + 2 * (qb - 1), hi = 4 + 2 * (qb + 2); if (lo < 4) lo = 4; if (hi > 36) hi = 36;
;                 if (is_ctx) { lo = 0; hi = 0; }
;                 attn_unit<2, 64, true>(lds, QC + (size_t)row0 * 256 + kv * 128, 256, KC + (size_t)(b * 2 + kv) * NKEY * 64, VCt + (size_t)(b * 2 + kv) * NKEY * 64,
;                                        4, lo, hi, 128 * qb, a.in[I_SINK][l * 4 + kv * 2] * LOG2E, a.in[I_SINK][l * 4 + kv * 2 + 1] * LOG2E, nullptr, 0.f, O + (size_t)row0 * DM + 768 + kv * 128, tid);
.LBB0_139:
	s_and_b64 vcc, exec, s[8:9]
	s_cbranch_vccz .LBB0_105
	s_lshl_b32 s3, s23, 1
	s_max_u32 s8, s3, 2
	s_min_u32 s3, s3, 28
	s_add_i32 s8, s8, 2
	s_add_i32 s3, s3, 8
	s_and_b64 s[0:1], s[0:1], exec
	s_cselect_b32 s25, 0, s8
	s_cselect_b32 s3, 0, s3
	s_ashr_i32 s21, s20, 31
	s_lshl_b64 s[0:1], s[20:21], 9
	v_readlane_b32 s8, v252, 45
	s_add_u32 s0, s8, s0
	v_readlane_b32 s8, v252, 46
	s_addc_u32 s1, s8, s1
	s_lshl_b32 s8, s16, 8
	s_add_u32 s10, s0, s8
	s_addc_u32 s11, s1, 0
	s_lshl_b32 s0, s24, 1
	s_add_i32 s0, s0, s16
	s_mul_hi_i32 s9, s0, 0x48000
	s_mul_i32 s8, s0, 0x48000
	v_readlane_b32 s0, v252, 51
	s_add_u32 s0, s0, s8
	v_readlane_b32 s1, v252, 52
	s_addc_u32 s1, s1, s9
	v_readlane_b32 s14, v252, 53
	s_add_u32 s8, s14, s8
	v_readlane_b32 s14, v252, 54
	s_addc_u32 s9, s14, s9
	s_lshl_b32 s14, s16, 1
	v_lshrrev_b32_e32 v0, 29, v178
	s_add_i32 s14, s14, s19
	v_add_u32_e32 v0, v176, v0
	s_ashr_i32 s15, s14, 31
	v_readlane_b32 s44, v252, 0
	v_ashrrev_i32_e32 v161, 31, v160
	v_ashrrev_i32_e32 v124, 3, v0
	v_and_b32_e32 v0, -8, v0
	s_lshl_b64 s[14:15], s[14:15], 2
	v_readlane_b32 s48, v252, 4
	s_waitcnt lgkmcnt(0)
	v_lshlrev_b64 v[2:3], 9, v[160:161]
	v_sub_u32_e32 v0, v176, v0
	v_readlane_b32 s49, v252, 5
	s_add_u32 s14, s48, s14
	v_lshl_add_u64 v[2:3], s[10:11], 0, v[2:3]
	v_mov_b32_e32 v163, v1
	v_ashrrev_i32_e32 v125, 31, v124
	s_nop 0
	v_lshlrev_b32_e32 v12, 3, v0
	s_addc_u32 s15, s49, s15
	v_lshl_add_u64 v[14:15], v[2:3], 0, v[162:163]
	v_lshlrev_b64 v[28:29], 7, v[124:125]
	v_ashrrev_i32_e32 v13, 31, v12
	global_load_dwordx2 v[114:115], v1, s[14:15]
	global_load_dwordx4 v[2:5], v[14:15], off
	global_load_dwordx4 v[6:9], v[14:15], off offset:64
	v_lshl_add_u64 v[10:11], s[0:1], 0, v[28:29]
	v_lshlrev_b64 v[26:27], 1, v[12:13]
	v_lshl_add_u64 v[12:13], s[8:9], 0, v[28:29]
	v_lshl_add_u64 v[10:11], v[10:11], 0, v[26:27]
	v_lshl_add_u64 v[12:13], v[12:13], 0, v[26:27]
	global_load_dwordx4 v[18:21], v[10:11], off
	global_load_dwordx4 v[22:25], v[12:13], off
	s_nop 0
	global_load_dwordx4 v[10:13], v[14:15], off offset:128
	s_nop 0
	global_load_dwordx4 v[14:17], v[14:15], off offset:192
	s_movk_i32 s10, 0x120
	s_sub_i32 s14, s3, s25
	v_mul_lo_u32 v30, v124, s10
	v_lshlrev_b32_e32 v0, 4, v0
	v_add3_u32 v129, 0, v30, v0
	s_cmp_lt_i32 s14, -2
	v_readlane_b32 s45, v252, 1
	v_readlane_b32 s46, v252, 2
	v_readlane_b32 s47, v252, 3
	v_readlane_b32 s50, v252, 6
	v_readlane_b32 s51, v252, 7
	s_waitcnt vmcnt(3)
	ds_write_b128 v129, v[18:21]
	s_waitcnt vmcnt(2)
	ds_write_b128 v129, v[22:25] offset:18432
	s_cbranch_scc1 .LBB0_142
	s_mov_b64 s[10:11], 0x2000
	v_lshl_add_u64 v[18:19], v[28:29], 0, s[10:11]
	v_lshl_add_u64 v[20:21], s[0:1], 0, v[18:19]
	v_lshl_add_u64 v[18:19], s[8:9], 0, v[18:19]
	v_lshl_add_u64 v[20:21], v[20:21], 0, v[26:27]
	v_lshl_add_u64 v[22:23], v[18:19], 0, v[26:27]
	global_load_dwordx4 v[18:21], v[20:21], off
	s_nop 0
	global_load_dwordx4 v[22:25], v[22:23], off
